# GEMM phases: static s_setprio 1 for the leading wave half (waves 0-3) instead of per-cluster flips (comparison of the two halves)
# speedup vs baseline: 1.0215x; 1.0007x over previous
.LBB0_87:
	s_andn2_b64 vcc, exec, s[0:1]
	s_cbranch_vccnz .LBB0_120
	v_readlane_b32 s0, v253, 29
	v_mov_b32_e32 v6, v179
	v_readlane_b32 s1, v253, 30
	s_andn2_b64 vcc, exec, s[0:1]
	v_readfirstlane_b32 s92, v6
	s_cbranch_vccnz .LBB0_120
	v_lshlrev_b32_e32 v3, 4, v6
	v_add_u32_e32 v1, 0x2000, v3
	v_ashrrev_i32_e32 v0, 31, v1
	v_lshrrev_b32_e32 v0, 22, v0
	v_add_u32_e32 v0, v1, v0
	v_ashrrev_i32_e32 v0, 10, v0
	v_mul_i32_i24_e32 v2, 0x400, v0
	v_sub_u32_e32 v1, v1, v2
	v_lshrrev_b32_e32 v2, 4, v1
	v_bitop3_b32 v2, v2, v1, 32 bitop3:0x6c
	v_ashrrev_i32_e32 v1, 31, v2
	v_lshrrev_b32_e32 v1, 26, v1
	v_add_u32_e32 v4, v2, v1
	v_lshlrev_b32_e32 v5, 3, v0
	v_ashrrev_i32_e32 v1, 6, v4
	v_and_b32_e32 v5, -16, v5
	v_add_u32_e32 v5, v1, v5
	v_and_b32_e32 v7, 3, v1
	s_mov_b32 s1, 0x7ffe0
	s_waitcnt vmcnt(0)
	v_lshrrev_b32_e32 v8, 2, v5
	v_lshlrev_b32_e32 v9, 1, v5
	v_and_b32_e32 v4, 0xc0, v4
	v_and_or_b32 v7, v5, s1, v7
	v_and_b32_e32 v8, 4, v8
	v_and_b32_e32 v9, 24, v9
	v_sub_u32_e32 v2, v2, v4
	v_or3_b32 v7, v7, v8, v9
	v_lshlrev_b32_e32 v8, 5, v0
	v_ashrrev_i16_sdwa v2, v181, sext(v2) dst_sel:DWORD dst_unused:UNUSED_PAD src0_sel:DWORD src1_sel:BYTE_0
	v_and_b32_e32 v8, 32, v8
	v_bfe_i32 v2, v2, 0, 16
	v_add_lshl_u32 v4, v8, v2, 1
	v_lshl_add_u32 v152, v7, 13, v4
	v_lshl_add_u32 v154, v5, 13, v4
	v_bfe_i32 v4, v6, 27, 1
	v_lshrrev_b32_e32 v4, 22, v4
	v_add_u32_e32 v4, v3, v4
	v_and_b32_e32 v4, 0xfffffc00, v4
	v_sub_u32_e32 v3, v3, v4
	v_lshrrev_b32_e32 v4, 4, v3
	v_bitop3_b32 v5, v4, v3, 32 bitop3:0x6c
	v_ashrrev_i32_e32 v4, 31, v6
	v_lshrrev_b32_e32 v4, 26, v4
	v_ashrrev_i32_e32 v3, 31, v3
	v_add_u32_e32 v4, v6, v4
	v_lshrrev_b32_e32 v3, 26, v3
	v_ashrrev_i32_e32 v4, 6, v4
	v_add_u32_e32 v3, v5, v3
	v_lshlrev_b32_e32 v7, 3, v4
	v_ashrrev_i32_e32 v3, 6, v3
	v_and_b32_e32 v7, -16, v7
	v_add_u32_e32 v7, v3, v7
	v_and_b32_e32 v8, 3, v3
	v_lshrrev_b32_e32 v9, 2, v7
	v_lshlrev_b32_e32 v10, 1, v7
	v_and_or_b32 v8, v7, s1, v8
	v_and_b32_e32 v9, 4, v9
	v_and_b32_e32 v10, 24, v10
	v_or3_b32 v8, v8, v9, v10
	v_mul_i32_i24_e32 v10, 64, v3
	v_sub_u32_e32 v5, v5, v10
	s_ashr_i32 s0, s92, 6
	v_lshlrev_b32_e32 v9, 5, v4
	v_ashrrev_i16_sdwa v5, v181, sext(v5) dst_sel:DWORD dst_unused:UNUSED_PAD src0_sel:DWORD src1_sel:BYTE_0
	s_lshl_b32 s54, s0, 10
	v_and_b32_e32 v9, 32, v9
	v_bfe_i32 v5, v5, 0, 16
	v_add_lshl_u32 v9, v9, v5, 1
	s_add_i32 s55, s54, 0
	v_readlane_b32 s2, v254, 35
	v_lshl_add_u32 v176, v8, 13, v9
	s_add_i32 m0, s55, 0x10000
	v_readlane_b32 s3, v254, 36
	v_lshl_add_u32 v156, v7, 13, v9
	s_add_i32 s56, s55, 0x2000
	s_add_i32 s57, s55, 0x4000
	s_add_i32 s58, s55, 0x6000
	s_load_dword s59, s[74:75], 0x0
	global_load_lds_dwordx4 v176, s[2:3]
	s_add_i32 m0, s55, 0x12000
	s_ashr_i32 s1, s92, 8
	global_load_lds_dwordx4 v152, s[2:3]
	v_readlane_b32 s2, v254, 31
	s_mov_b32 m0, s55
	v_readlane_b32 s3, v254, 32
	s_nop 4
	global_load_lds_dwordx4 v156, s[2:3]
	s_mov_b32 m0, s56
	s_nop 0
	global_load_lds_dwordx4 v154, s[2:3]
	v_readlane_b32 s2, v254, 29
	s_add_i32 m0, s55, 0x14000
	v_readlane_b32 s3, v254, 30
	s_nop 4
	global_load_lds_dwordx4 v176, s[2:3]
	s_add_i32 m0, s55, 0x16000
	s_cmp_lg_u32 s1, 1
	global_load_lds_dwordx4 v152, s[2:3]
	v_readlane_b32 s2, v254, 33
	s_mov_b32 m0, s57
	v_readlane_b32 s3, v254, 34
	s_nop 4
	global_load_lds_dwordx4 v156, s[2:3]
	s_mov_b32 m0, s58
	s_nop 0
	global_load_lds_dwordx4 v154, s[2:3]
	s_setprio 1
	s_cbranch_scc1 .LBB0_91
	s_barrier
	s_setprio 0

.LBB0_135:
	s_or_b64 exec, exec, s[0:1]
	v_readlane_b32 s0, v253, 33
	v_mov_b32_e32 v6, v179
	v_readlane_b32 s1, v253, 34
	s_waitcnt lgkmcnt(0)
	s_barrier
	s_andn2_b64 vcc, exec, s[0:1]
	v_readfirstlane_b32 s92, v6
	s_cbranch_vccnz .LBB0_155
	v_lshlrev_b32_e32 v3, 4, v6
	v_add_u32_e32 v1, 0x2000, v3
	v_ashrrev_i32_e32 v0, 31, v1
	v_lshrrev_b32_e32 v0, 22, v0
	v_add_u32_e32 v0, v1, v0
	v_ashrrev_i32_e32 v0, 10, v0
	v_mul_i32_i24_e32 v2, 0x400, v0
	v_sub_u32_e32 v1, v1, v2
	v_lshrrev_b32_e32 v2, 4, v1
	v_bitop3_b32 v2, v2, v1, 32 bitop3:0x6c
	v_ashrrev_i32_e32 v1, 31, v2
	v_lshrrev_b32_e32 v1, 26, v1
	v_add_u32_e32 v4, v2, v1
	v_lshlrev_b32_e32 v5, 3, v0
	v_ashrrev_i32_e32 v1, 6, v4
	v_and_b32_e32 v5, -16, v5
	v_add_u32_e32 v5, v1, v5
	v_and_b32_e32 v7, 3, v1
	s_mov_b32 s0, 0x1fffe0
	s_waitcnt vmcnt(0)
	v_lshrrev_b32_e32 v8, 2, v5
	v_lshlrev_b32_e32 v9, 1, v5
	v_and_b32_e32 v4, 0xc0, v4
	v_and_or_b32 v7, v5, s0, v7
	v_and_b32_e32 v8, 4, v8
	v_and_b32_e32 v9, 24, v9
	v_sub_u32_e32 v2, v2, v4
	v_or3_b32 v7, v7, v8, v9
	v_lshlrev_b32_e32 v8, 5, v0
	v_ashrrev_i16_sdwa v2, v181, sext(v2) dst_sel:DWORD dst_unused:UNUSED_PAD src0_sel:DWORD src1_sel:BYTE_0
	v_and_b32_e32 v8, 32, v8
	v_bfe_i32 v2, v2, 0, 16
	v_add_lshl_u32 v4, v8, v2, 1
	v_lshl_add_u32 v144, v7, 11, v4
	v_lshl_add_u32 v146, v5, 11, v4
	v_bfe_i32 v4, v6, 27, 1
	v_lshrrev_b32_e32 v4, 22, v4
	v_add_u32_e32 v4, v3, v4
	v_and_b32_e32 v4, 0xfffffc00, v4
	v_sub_u32_e32 v3, v3, v4
	v_lshrrev_b32_e32 v4, 4, v3
	v_bitop3_b32 v5, v4, v3, 32 bitop3:0x6c
	v_ashrrev_i32_e32 v4, 31, v6
	v_lshrrev_b32_e32 v4, 26, v4
	v_ashrrev_i32_e32 v3, 31, v3
	v_add_u32_e32 v4, v6, v4
	v_lshrrev_b32_e32 v3, 26, v3
	v_ashrrev_i32_e32 v4, 6, v4
	v_add_u32_e32 v3, v5, v3
	v_lshlrev_b32_e32 v7, 3, v4
	v_ashrrev_i32_e32 v3, 6, v3
	v_and_b32_e32 v7, -16, v7
	v_add_u32_e32 v7, v3, v7
	v_and_b32_e32 v8, 3, v3
	v_lshrrev_b32_e32 v9, 2, v7
	v_lshlrev_b32_e32 v10, 1, v7
	v_and_or_b32 v8, v7, s0, v8
	v_and_b32_e32 v9, 4, v9
	v_and_b32_e32 v10, 24, v10
	v_or3_b32 v8, v8, v9, v10
	v_mul_i32_i24_e32 v10, 64, v3
	v_sub_u32_e32 v5, v5, v10
	s_ashr_i32 s1, s92, 6
	v_lshlrev_b32_e32 v9, 5, v4
	v_ashrrev_i16_sdwa v5, v181, sext(v5) dst_sel:DWORD dst_unused:UNUSED_PAD src0_sel:DWORD src1_sel:BYTE_0
	s_lshl_b32 s56, s1, 10
	v_and_b32_e32 v9, 32, v9
	v_bfe_i32 v5, v5, 0, 16
	v_add_lshl_u32 v9, v9, v5, 1
	s_add_i32 s57, s56, 0
	v_readlane_b32 s2, v254, 6
	v_lshl_add_u32 v176, v8, 11, v9
	s_add_i32 m0, s57, 0x10000
	v_readlane_b32 s3, v254, 7
	v_lshl_add_u32 v148, v7, 11, v9
	s_add_i32 s58, s57, 0x2000
	s_add_i32 s7, s57, 0x4000
	s_add_i32 s15, s57, 0x6000
	s_ashr_i32 s0, s92, 8
	global_load_lds_dwordx4 v176, s[2:3]
	s_add_i32 m0, s57, 0x12000
	s_nop 0
	global_load_lds_dwordx4 v144, s[2:3]
	v_readlane_b32 s2, v254, 2
	s_mov_b32 m0, s57
	v_readlane_b32 s3, v254, 3
	s_nop 4
	global_load_lds_dwordx4 v148, s[2:3]
	s_mov_b32 m0, s58
	s_nop 0
	global_load_lds_dwordx4 v146, s[2:3]
	v_readlane_b32 s2, v254, 0
	s_add_i32 m0, s57, 0x14000
	v_readlane_b32 s3, v254, 1
	s_nop 4
	global_load_lds_dwordx4 v176, s[2:3]
	s_add_i32 m0, s57, 0x16000
	s_cmp_lg_u32 s0, 1
	global_load_lds_dwordx4 v144, s[2:3]
	v_readlane_b32 s2, v254, 4
	s_mov_b32 m0, s7
	v_readlane_b32 s3, v254, 5
	s_nop 4
	global_load_lds_dwordx4 v148, s[2:3]
	s_mov_b32 m0, s15
	s_nop 0
	global_load_lds_dwordx4 v146, s[2:3]
	s_setprio 1
	s_cbranch_scc1 .LBB0_138
	s_barrier
	s_setprio 0

.LBB0_156:
	s_and_b64 vcc, exec, s[0:1]
	s_cbranch_vccz .LBB0_191
	v_readlane_b32 s0, v255, 25
	s_cmp_eq_u32 s0, 4
	s_cbranch_scc0 .LBB0_190
	v_readlane_b32 s0, v253, 29
	v_mov_b32_e32 v6, v179
	v_readlane_b32 s1, v253, 30
	s_andn2_b64 vcc, exec, s[0:1]
	v_readfirstlane_b32 s94, v6
	s_cbranch_vccnz .LBB0_190
	v_lshlrev_b32_e32 v3, 4, v6
	s_waitcnt lgkmcnt(0)
	v_add_u32_e32 v1, 0x2000, v3
	v_ashrrev_i32_e32 v0, 31, v1
	v_lshrrev_b32_e32 v0, 22, v0
	v_add_u32_e32 v0, v1, v0
	v_ashrrev_i32_e32 v0, 10, v0
	v_mul_i32_i24_e32 v2, 0x400, v0
	v_sub_u32_e32 v1, v1, v2
	v_lshrrev_b32_e32 v2, 4, v1
	v_bitop3_b32 v2, v2, v1, 32 bitop3:0x6c
	v_ashrrev_i32_e32 v1, 31, v2
	v_lshrrev_b32_e32 v1, 26, v1
	v_add_u32_e32 v4, v2, v1
	v_lshlrev_b32_e32 v5, 3, v0
	v_ashrrev_i32_e32 v1, 6, v4
	v_and_b32_e32 v5, -16, v5
	v_add_u32_e32 v5, v1, v5
	v_and_b32_e32 v7, 3, v1
	s_mov_b32 s1, 0x1fffe0
	s_waitcnt vmcnt(0)
	v_lshrrev_b32_e32 v8, 2, v5
	v_lshlrev_b32_e32 v9, 1, v5
	v_and_b32_e32 v4, 0xc0, v4
	v_and_or_b32 v7, v5, s1, v7
	v_and_b32_e32 v8, 4, v8
	v_and_b32_e32 v9, 24, v9
	v_sub_u32_e32 v2, v2, v4
	v_or3_b32 v7, v7, v8, v9
	v_lshlrev_b32_e32 v8, 5, v0
	v_ashrrev_i16_sdwa v2, v181, sext(v2) dst_sel:DWORD dst_unused:UNUSED_PAD src0_sel:DWORD src1_sel:BYTE_0
	v_and_b32_e32 v8, 32, v8
	v_bfe_i32 v2, v2, 0, 16
	v_add_lshl_u32 v4, v8, v2, 1
	v_lshl_add_u32 v198, v7, 11, v4
	v_lshl_add_u32 v200, v5, 11, v4
	v_bfe_i32 v4, v6, 27, 1
	v_lshrrev_b32_e32 v4, 22, v4
	v_add_u32_e32 v4, v3, v4
	v_and_b32_e32 v4, 0xfffffc00, v4
	v_sub_u32_e32 v3, v3, v4
	v_lshrrev_b32_e32 v4, 4, v3
	v_bitop3_b32 v5, v4, v3, 32 bitop3:0x6c
	v_ashrrev_i32_e32 v4, 31, v6
	v_lshrrev_b32_e32 v4, 26, v4
	v_ashrrev_i32_e32 v3, 31, v3
	v_add_u32_e32 v4, v6, v4
	v_lshrrev_b32_e32 v3, 26, v3
	v_ashrrev_i32_e32 v4, 6, v4
	v_add_u32_e32 v3, v5, v3
	v_lshlrev_b32_e32 v7, 3, v4
	v_ashrrev_i32_e32 v3, 6, v3
	v_and_b32_e32 v7, -16, v7
	v_add_u32_e32 v7, v3, v7
	v_and_b32_e32 v8, 3, v3
	v_lshrrev_b32_e32 v9, 2, v7
	v_lshlrev_b32_e32 v10, 1, v7
	v_and_or_b32 v8, v7, s1, v8
	v_and_b32_e32 v9, 4, v9
	v_and_b32_e32 v10, 24, v10
	v_or3_b32 v8, v8, v9, v10
	v_mul_i32_i24_e32 v10, 64, v3
	v_sub_u32_e32 v5, v5, v10
	s_ashr_i32 s0, s94, 6
	v_lshlrev_b32_e32 v9, 5, v4
	v_ashrrev_i16_sdwa v5, v181, sext(v5) dst_sel:DWORD dst_unused:UNUSED_PAD src0_sel:DWORD src1_sel:BYTE_0
	s_lshl_b32 s54, s0, 10
	v_and_b32_e32 v9, 32, v9
	v_bfe_i32 v5, v5, 0, 16
	v_add_lshl_u32 v9, v9, v5, 1
	s_add_i32 s55, s54, 0
	v_readlane_b32 s2, v254, 51
	v_lshl_add_u32 v176, v8, 11, v9
	s_add_i32 m0, s55, 0x10000
	v_readlane_b32 s3, v254, 52
	v_lshl_add_u32 v202, v7, 11, v9
	s_add_i32 s56, s55, 0x2000
	s_add_i32 s7, s55, 0x4000
	s_add_i32 s15, s55, 0x6000
	s_load_dword s95, s[74:75], 0x0
	global_load_lds_dwordx4 v176, s[2:3]
	s_add_i32 m0, s55, 0x12000
	s_ashr_i32 s1, s94, 8
	global_load_lds_dwordx4 v198, s[2:3]
	v_readlane_b32 s2, v254, 47
	s_mov_b32 m0, s55
	v_readlane_b32 s3, v254, 48
	s_nop 4
	global_load_lds_dwordx4 v202, s[2:3]
	s_mov_b32 m0, s56
	s_nop 0
	global_load_lds_dwordx4 v200, s[2:3]
	v_readlane_b32 s2, v254, 45
	s_add_i32 m0, s55, 0x14000
	v_readlane_b32 s3, v254, 46
	s_nop 4
	global_load_lds_dwordx4 v176, s[2:3]
	s_add_i32 m0, s55, 0x16000
	s_cmp_lg_u32 s1, 1
	global_load_lds_dwordx4 v198, s[2:3]
	v_readlane_b32 s2, v254, 49
	s_mov_b32 m0, s7
	v_readlane_b32 s3, v254, 50
	s_nop 4
	global_load_lds_dwordx4 v202, s[2:3]
	s_mov_b32 m0, s15
	s_nop 0
	global_load_lds_dwordx4 v200, s[2:3]
	s_setprio 1
	s_cbranch_scc1 .LBB0_161
	s_barrier
	s_setprio 0

.LBB0_279:
	s_andn2_b64 vcc, exec, s[0:1]
	s_cbranch_vccnz .LBB0_22
	v_readlane_b32 s0, v255, 25
	s_cmp_gt_i32 s0, 0
	s_mov_b64 s[0:1], -1
	s_cbranch_scc0 .LBB0_298
	v_readlane_b32 s0, v253, 42
	s_waitcnt lgkmcnt(0)
	v_mov_b32_e32 v1, v179
	v_readlane_b32 s1, v253, 43
	s_andn2_b64 vcc, exec, s[0:1]
	v_readfirstlane_b32 s3, v1
	s_cbranch_vccnz .LBB0_297
	v_lshlrev_b32_e32 v4, 4, v1
	v_add_u32_e32 v2, 0x2000, v4
	v_ashrrev_i32_e32 v0, 31, v2
	v_lshrrev_b32_e32 v0, 22, v0
	v_add_u32_e32 v0, v2, v0
	v_ashrrev_i32_e32 v0, 10, v0
	v_mul_i32_i24_e32 v3, 0x400, v0
	v_sub_u32_e32 v2, v2, v3
	v_lshrrev_b32_e32 v3, 4, v2
	v_bitop3_b32 v3, v3, v2, 32 bitop3:0x6c
	v_ashrrev_i32_e32 v2, 31, v3
	v_lshrrev_b32_e32 v2, 26, v2
	v_add_u32_e32 v5, v3, v2
	v_lshlrev_b32_e32 v6, 3, v0
	v_ashrrev_i32_e32 v2, 6, v5
	v_and_b32_e32 v6, -16, v6
	v_add_u32_e32 v6, v2, v6
	v_and_b32_e32 v7, 3, v2
	s_mov_b32 s1, 0x1fffe0
	s_waitcnt vmcnt(0)
	v_lshrrev_b32_e32 v8, 2, v6
	v_lshlrev_b32_e32 v9, 1, v6
	v_and_b32_e32 v5, 0xc0, v5
	v_and_or_b32 v7, v6, s1, v7
	v_and_b32_e32 v8, 4, v8
	v_and_b32_e32 v9, 24, v9
	v_sub_u32_e32 v3, v3, v5
	v_or3_b32 v7, v7, v8, v9
	v_lshlrev_b32_e32 v8, 5, v0
	v_ashrrev_i16_sdwa v3, v181, sext(v3) dst_sel:DWORD dst_unused:UNUSED_PAD src0_sel:DWORD src1_sel:BYTE_0
	v_and_b32_e32 v8, 32, v8
	v_bfe_i32 v3, v3, 0, 16
	v_add_lshl_u32 v5, v8, v3, 1
	v_lshl_add_u32 v128, v7, 11, v5
	v_lshl_add_u32 v130, v6, 11, v5
	v_bfe_i32 v5, v1, 27, 1
	v_lshrrev_b32_e32 v5, 22, v5
	v_add_u32_e32 v5, v4, v5
	v_and_b32_e32 v5, 0xfffffc00, v5
	v_sub_u32_e32 v4, v4, v5
	v_lshrrev_b32_e32 v5, 4, v4
	v_bitop3_b32 v6, v5, v4, 32 bitop3:0x6c
	v_ashrrev_i32_e32 v5, 31, v1
	v_lshrrev_b32_e32 v5, 26, v5
	v_ashrrev_i32_e32 v4, 31, v4
	v_add_u32_e32 v5, v1, v5
	v_lshrrev_b32_e32 v4, 26, v4
	v_ashrrev_i32_e32 v5, 6, v5
	v_add_u32_e32 v4, v6, v4
	v_lshlrev_b32_e32 v7, 3, v5
	v_ashrrev_i32_e32 v4, 6, v4
	v_and_b32_e32 v7, -16, v7
	v_add_u32_e32 v7, v4, v7
	v_and_b32_e32 v8, 3, v4
	v_lshrrev_b32_e32 v9, 2, v7
	v_lshlrev_b32_e32 v10, 1, v7
	v_and_or_b32 v8, v7, s1, v8
	v_and_b32_e32 v9, 4, v9
	v_and_b32_e32 v10, 24, v10
	v_or3_b32 v8, v8, v9, v10
	v_mul_i32_i24_e32 v10, 64, v4
	v_sub_u32_e32 v6, v6, v10
	s_ashr_i32 s0, s3, 6
	v_lshlrev_b32_e32 v9, 5, v5
	v_ashrrev_i16_sdwa v6, v181, sext(v6) dst_sel:DWORD dst_unused:UNUSED_PAD src0_sel:DWORD src1_sel:BYTE_0
	s_lshl_b32 s6, s0, 10
	v_and_b32_e32 v9, 32, v9
	v_bfe_i32 v6, v6, 0, 16
	v_add_lshl_u32 v9, v9, v6, 1
	s_add_i32 s7, s6, 0
	v_readlane_b32 s20, v254, 23
	v_lshl_add_u32 v176, v8, 11, v9
	s_add_i32 m0, s7, 0x10000
	v_readlane_b32 s21, v254, 24
	v_lshl_add_u32 v132, v7, 11, v9
	s_add_i32 s9, s7, 0x2000
	s_add_i32 s15, s7, 0x4000
	s_add_i32 s34, s7, 0x6000
	s_load_dword s50, s[74:75], 0x0
	global_load_lds_dwordx4 v176, s[20:21]
	s_add_i32 m0, s7, 0x12000
	s_ashr_i32 s1, s3, 8
	global_load_lds_dwordx4 v128, s[20:21]
	v_readlane_b32 s20, v254, 19
	s_mov_b32 m0, s7
	v_readlane_b32 s21, v254, 20
	s_nop 4
	global_load_lds_dwordx4 v132, s[20:21]
	s_mov_b32 m0, s9
	s_nop 0
	global_load_lds_dwordx4 v130, s[20:21]
	v_readlane_b32 s20, v254, 17
	s_add_i32 m0, s7, 0x14000
	v_readlane_b32 s21, v254, 18
	s_nop 4
	global_load_lds_dwordx4 v176, s[20:21]
	s_add_i32 m0, s7, 0x16000
	s_cmp_lg_u32 s1, 1
	global_load_lds_dwordx4 v128, s[20:21]
	v_readlane_b32 s20, v254, 21
	s_mov_b32 m0, s15
	v_readlane_b32 s21, v254, 22
	s_nop 4
	global_load_lds_dwordx4 v132, s[20:21]
	s_mov_b32 m0, s34
	s_nop 0
	global_load_lds_dwordx4 v130, s[20:21]
	s_setprio 1
	s_cbranch_scc1 .LBB0_284
	s_barrier
	s_setprio 0
